# br0 PV rewritten straight-line: 8 V-fragment reads hoisted, 3 variants by active query tiles
# speedup vs baseline: 1.0185x; 1.0050x over previous
; #define LAS __attribute__((address_space(3)))
; DI f32x4 mfma16(bf16x8 a, bf16x8 b, f32x4 c) { return __builtin_amdgcn_mfma_f32_16x16x32_bf16(a, b, c, 0, 0, 0); }
; DI void nsa_attn_phase(const int tid0, LAS unsigned char* lds, const P& p, int G, int c) {
;     ...
; #pragma unroll
;                 for (int h = 0; h < 2; ++h) {
;                     LAS bf16_t* VtT = Tc + h * 9216 + 4608;
;                     if (act[h][0] || act[h][1]) {
; #pragma unroll
;                         for (int s = 0; s < 2; ++s)
; #pragma unroll
;                             for (int dt = 0; dt < 4; ++dt) { u32x4 t; const u32x2 v0 = *(const LAS u32x2*)(VtT + (dt * 16 + fr) * 72 + s * 32 + fq * 4), v1 = *(const LAS u32x2*)(VtT + (dt * 16 + fr) * 72 + s * 32 + 16 + fq * 4);
;                                 t.x = v0.x; t.y = v0.y; t.z = v1.x; t.w = v1.y; const bf16x8 vf = __builtin_bit_cast(bf16x8, t);
; #pragma unroll
;                                 for (int qt = 0; qt < 2; ++qt) if (act[h][qt]) O[dt][qt] = mfma16(vf, pf[h][s][qt], O[dt][qt]); } }
.LBB0_272:
	s_and_b64 s[0:1], s[8:9], exec
	s_movk_i32 s0, 0x2400
	s_cselect_b32 s0, 0x14000, s0
	v_add3_u32 v157, s0, v179, v180
	v_add_u32_e32 v170, 0x800, v157
	v_add_u32_e32 v171, 0x1000, v157
	v_add_u32_e32 v185, 0x1800, v157
	ds_read2_b64 v[162:165], v157 offset1:4
	ds_read2_b64 v[166:169], v170 offset0:32 offset1:36
	ds_read2_b64 v[206:209], v171 offset0:64 offset1:68
	ds_read2_b64 v[214:217], v185 offset0:96 offset1:100
	ds_read2_b64 v[218:221], v157 offset0:8 offset1:12
	ds_read2_b64 v[222:225], v170 offset0:40 offset1:44
	ds_read2_b64 v[226:229], v171 offset0:72 offset1:76
	ds_read2_b64 v[238:241], v185 offset0:104 offset1:108
	s_and_b64 vcc, exec, s[4:5]
	s_cbranch_vccz .Lpv0_only1
	s_and_b64 vcc, exec, s[10:11]
	s_cbranch_vccz .Lpv0_only0
	s_waitcnt lgkmcnt(7)
	v_mfma_f32_16x16x32_bf16 v[92:95], v[162:165], v[118:121], v[92:95]
	v_mfma_f32_16x16x32_bf16 v[76:79], v[162:165], v[126:129], v[76:79]
	s_waitcnt lgkmcnt(6)
	v_mfma_f32_16x16x32_bf16 v[88:91], v[166:169], v[118:121], v[88:91]
	v_mfma_f32_16x16x32_bf16 v[72:75], v[166:169], v[126:129], v[72:75]
	s_waitcnt lgkmcnt(5)
	v_mfma_f32_16x16x32_bf16 v[84:87], v[206:209], v[118:121], v[84:87]
	v_mfma_f32_16x16x32_bf16 v[68:71], v[206:209], v[126:129], v[68:71]
	s_waitcnt lgkmcnt(4)
	v_mfma_f32_16x16x32_bf16 v[80:83], v[214:217], v[118:121], v[80:83]
	v_mfma_f32_16x16x32_bf16 v[64:67], v[214:217], v[126:129], v[64:67]
	s_waitcnt lgkmcnt(3)
	v_mfma_f32_16x16x32_bf16 v[92:95], v[218:221], v[114:117], v[92:95]
	v_mfma_f32_16x16x32_bf16 v[76:79], v[218:221], v[122:125], v[76:79]
	s_waitcnt lgkmcnt(2)
	v_mfma_f32_16x16x32_bf16 v[88:91], v[222:225], v[114:117], v[88:91]
	v_mfma_f32_16x16x32_bf16 v[72:75], v[222:225], v[122:125], v[72:75]
	s_waitcnt lgkmcnt(1)
	v_mfma_f32_16x16x32_bf16 v[84:87], v[226:229], v[114:117], v[84:87]
	v_mfma_f32_16x16x32_bf16 v[68:71], v[226:229], v[122:125], v[68:71]
	s_waitcnt lgkmcnt(0)
	v_mfma_f32_16x16x32_bf16 v[80:83], v[238:241], v[114:117], v[80:83]
	v_mfma_f32_16x16x32_bf16 v[64:67], v[238:241], v[122:125], v[64:67]
	s_branch .LBB0_304
.Lpv0_only0:
	s_waitcnt lgkmcnt(7)
	v_mfma_f32_16x16x32_bf16 v[92:95], v[162:165], v[118:121], v[92:95]
	s_waitcnt lgkmcnt(6)
	v_mfma_f32_16x16x32_bf16 v[88:91], v[166:169], v[118:121], v[88:91]
	s_waitcnt lgkmcnt(5)
	v_mfma_f32_16x16x32_bf16 v[84:87], v[206:209], v[118:121], v[84:87]
	s_waitcnt lgkmcnt(4)
	v_mfma_f32_16x16x32_bf16 v[80:83], v[214:217], v[118:121], v[80:83]
	s_waitcnt lgkmcnt(3)
	v_mfma_f32_16x16x32_bf16 v[92:95], v[218:221], v[114:117], v[92:95]
	s_waitcnt lgkmcnt(2)
	v_mfma_f32_16x16x32_bf16 v[88:91], v[222:225], v[114:117], v[88:91]
	s_waitcnt lgkmcnt(1)
	v_mfma_f32_16x16x32_bf16 v[84:87], v[226:229], v[114:117], v[84:87]
	s_waitcnt lgkmcnt(0)
	v_mfma_f32_16x16x32_bf16 v[80:83], v[238:241], v[114:117], v[80:83]
	s_branch .LBB0_304
.Lpv0_only1:
	s_waitcnt lgkmcnt(7)
	v_mfma_f32_16x16x32_bf16 v[76:79], v[162:165], v[126:129], v[76:79]
	s_waitcnt lgkmcnt(6)
	v_mfma_f32_16x16x32_bf16 v[72:75], v[166:169], v[126:129], v[72:75]
	s_waitcnt lgkmcnt(5)
	v_mfma_f32_16x16x32_bf16 v[68:71], v[206:209], v[126:129], v[68:71]
	s_waitcnt lgkmcnt(4)
	v_mfma_f32_16x16x32_bf16 v[64:67], v[214:217], v[126:129], v[64:67]
	s_waitcnt lgkmcnt(3)
	v_mfma_f32_16x16x32_bf16 v[76:79], v[218:221], v[122:125], v[76:79]
	s_waitcnt lgkmcnt(2)
	v_mfma_f32_16x16x32_bf16 v[72:75], v[222:225], v[122:125], v[72:75]
	s_waitcnt lgkmcnt(1)
	v_mfma_f32_16x16x32_bf16 v[68:71], v[226:229], v[122:125], v[68:71]
	s_waitcnt lgkmcnt(0)
	v_mfma_f32_16x16x32_bf16 v[64:67], v[238:241], v[122:125], v[64:67]
; #define LAS __attribute__((address_space(3)))
; DI f32x4 mfma16(bf16x8 a, bf16x8 b, f32x4 c) { return __builtin_amdgcn_mfma_f32_16x16x32_bf16(a, b, c, 0, 0, 0); }
; DI void nsa_attn_phase(const int tid0, LAS unsigned char* lds, const P& p, int G, int c) {
;     ...
; #pragma unroll
;                 for (int h = 0; h < 2; ++h) {
;                     LAS bf16_t* VtT = Tc + h * 9216 + 4608;
;                     if (act[h][0] || act[h][1]) {
; #pragma unroll
;                         for (int s = 0; s < 2; ++s)
; #pragma unroll
;                             for (int dt = 0; dt < 4; ++dt) { u32x4 t; const u32x2 v0 = *(const LAS u32x2*)(VtT + (dt * 16 + fr) * 72 + s * 32 + fq * 4), v1 = *(const LAS u32x2*)(VtT + (dt * 16 + fr) * 72 + s * 32 + 16 + fq * 4);
;                                 t.x = v0.x; t.y = v0.y; t.z = v1.x; t.w = v1.y; const bf16x8 vf = __builtin_bit_cast(bf16x8, t);
; #pragma unroll
;                                 for (int qt = 0; qt < 2; ++qt) if (act[h][qt]) O[dt][qt] = mfma16(vf, pf[h][s][qt], O[dt][qt]); } }
.LBB0_304:
	s_or_b64 s[0:1], s[14:15], s[12:13]
	s_andn2_b64 vcc, exec, s[0:1]
	s_cbranch_vccnz .LBB0_337
	s_and_b64 s[0:1], s[8:9], exec
	s_movk_i32 s0, 0x6c00
	s_cselect_b32 s0, 0x18800, s0
	v_add3_u32 v157, s0, v179, v180
	v_add_u32_e32 v170, 0x800, v157
	v_add_u32_e32 v171, 0x1000, v157
	v_add_u32_e32 v185, 0x1800, v157
	ds_read2_b64 v[162:165], v157 offset1:4
	ds_read2_b64 v[166:169], v170 offset0:32 offset1:36
	ds_read2_b64 v[206:209], v171 offset0:64 offset1:68
	ds_read2_b64 v[214:217], v185 offset0:96 offset1:100
	ds_read2_b64 v[218:221], v157 offset0:8 offset1:12
	ds_read2_b64 v[222:225], v170 offset0:40 offset1:44
	ds_read2_b64 v[226:229], v171 offset0:72 offset1:76
	ds_read2_b64 v[238:241], v185 offset0:104 offset1:108
	s_and_b64 vcc, exec, s[14:15]
	s_cbranch_vccz .Lpv1_only1
	s_and_b64 vcc, exec, s[12:13]
	s_cbranch_vccz .Lpv1_only0
	s_waitcnt lgkmcnt(7)
	v_mfma_f32_16x16x32_bf16 v[92:95], v[162:165], v[134:137], v[92:95]
	v_mfma_f32_16x16x32_bf16 v[76:79], v[162:165], v[138:141], v[76:79]
	s_waitcnt lgkmcnt(6)
	v_mfma_f32_16x16x32_bf16 v[88:91], v[166:169], v[134:137], v[88:91]
	v_mfma_f32_16x16x32_bf16 v[72:75], v[166:169], v[138:141], v[72:75]
	s_waitcnt lgkmcnt(5)
	v_mfma_f32_16x16x32_bf16 v[84:87], v[206:209], v[134:137], v[84:87]
	v_mfma_f32_16x16x32_bf16 v[68:71], v[206:209], v[138:141], v[68:71]
	s_waitcnt lgkmcnt(4)
	v_mfma_f32_16x16x32_bf16 v[80:83], v[214:217], v[134:137], v[80:83]
	v_mfma_f32_16x16x32_bf16 v[64:67], v[214:217], v[138:141], v[64:67]
	s_waitcnt lgkmcnt(3)
	v_mfma_f32_16x16x32_bf16 v[92:95], v[218:221], v[130:133], v[92:95]
	v_mfma_f32_16x16x32_bf16 v[76:79], v[218:221], v[0:3], v[76:79]
	s_waitcnt lgkmcnt(2)
	v_mfma_f32_16x16x32_bf16 v[88:91], v[222:225], v[130:133], v[88:91]
	v_mfma_f32_16x16x32_bf16 v[72:75], v[222:225], v[0:3], v[72:75]
	s_waitcnt lgkmcnt(1)
	v_mfma_f32_16x16x32_bf16 v[84:87], v[226:229], v[130:133], v[84:87]
	v_mfma_f32_16x16x32_bf16 v[68:71], v[226:229], v[0:3], v[68:71]
	s_waitcnt lgkmcnt(0)
	v_mfma_f32_16x16x32_bf16 v[80:83], v[238:241], v[130:133], v[80:83]
	v_mfma_f32_16x16x32_bf16 v[64:67], v[238:241], v[0:3], v[64:67]
	s_branch .LBB0_337
.Lpv1_only0:
	s_waitcnt lgkmcnt(7)
	v_mfma_f32_16x16x32_bf16 v[92:95], v[162:165], v[134:137], v[92:95]
	s_waitcnt lgkmcnt(6)
	v_mfma_f32_16x16x32_bf16 v[88:91], v[166:169], v[134:137], v[88:91]
	s_waitcnt lgkmcnt(5)
	v_mfma_f32_16x16x32_bf16 v[84:87], v[206:209], v[134:137], v[84:87]
	s_waitcnt lgkmcnt(4)
	v_mfma_f32_16x16x32_bf16 v[80:83], v[214:217], v[134:137], v[80:83]
	s_waitcnt lgkmcnt(3)
	v_mfma_f32_16x16x32_bf16 v[92:95], v[218:221], v[130:133], v[92:95]
	s_waitcnt lgkmcnt(2)
	v_mfma_f32_16x16x32_bf16 v[88:91], v[222:225], v[130:133], v[88:91]
	s_waitcnt lgkmcnt(1)
	v_mfma_f32_16x16x32_bf16 v[84:87], v[226:229], v[130:133], v[84:87]
	s_waitcnt lgkmcnt(0)
	v_mfma_f32_16x16x32_bf16 v[80:83], v[238:241], v[130:133], v[80:83]
	s_branch .LBB0_337
.Lpv1_only1:
	s_waitcnt lgkmcnt(7)
	v_mfma_f32_16x16x32_bf16 v[76:79], v[162:165], v[138:141], v[76:79]
	s_waitcnt lgkmcnt(6)
	v_mfma_f32_16x16x32_bf16 v[72:75], v[166:169], v[138:141], v[72:75]
	s_waitcnt lgkmcnt(5)
	v_mfma_f32_16x16x32_bf16 v[68:71], v[206:209], v[138:141], v[68:71]
	s_waitcnt lgkmcnt(4)
	v_mfma_f32_16x16x32_bf16 v[64:67], v[214:217], v[138:141], v[64:67]
	s_waitcnt lgkmcnt(3)
	v_mfma_f32_16x16x32_bf16 v[76:79], v[218:221], v[0:3], v[76:79]
	s_waitcnt lgkmcnt(2)
	v_mfma_f32_16x16x32_bf16 v[72:75], v[222:225], v[0:3], v[72:75]
	s_waitcnt lgkmcnt(1)
	v_mfma_f32_16x16x32_bf16 v[68:71], v[226:229], v[0:3], v[68:71]
	s_waitcnt lgkmcnt(0)
	v_mfma_f32_16x16x32_bf16 v[64:67], v[238:241], v[0:3], v[64:67]
